# v27 + MLP-out main residual epilogue: bf16 residual row loads issued three row groups ahead into free VGPRs with counted vmcnt waits (hipcc had each load waited immediately)
# baseline (speedup 1.0000x reference)
.LBB0_1511:
	s_lshl_b32 s4, s17, 8
	s_ashr_i32 s17, s21, 2
	s_andn2_b32 s17, s17, 63
	v_and_b32_e32 v188, 15, v186
	s_add_i32 s21, s17, s4
	v_or_b32_e32 v174, s21, v188
	v_ashrrev_i32_e32 v175, 31, v174
	v_lshlrev_b64 v[146:147], 11, v[174:175]
	v_lshl_add_u64 v[178:179], v[146:147], 0, v[162:163]
	v_lshl_add_u64 v[180:181], v[178:179], 1, s[50:51]
	s_mov_b32 s101, 0
	global_load_dwordx4 v[234:237], v[180:181], off
	s_nop 0
	global_load_dwordx4 v[238:241], v[180:181], off offset:256
	s_mov_b32 s100, 0x10000
	v_lshl_add_u64 v[216:217], v[180:181], 0, s[100:101]
	global_load_dwordx4 v[242:245], v[216:217], off
	s_nop 0
	global_load_dwordx4 v[246:249], v[216:217], off offset:256
	s_mov_b32 s100, 0x20000
	v_lshl_add_u64 v[232:233], v[180:181], 0, s[100:101]
	global_load_dwordx4 v[208:211], v[232:233], off
	s_nop 0
	global_load_dwordx4 v[212:215], v[232:233], off offset:256
	s_mov_b64 s[26:27], -1
	s_and_b64 vcc, exec, s[94:95]
	s_waitcnt vmcnt(4)
	v_lshlrev_b32_e32 v176, 16, v234
	v_and_b32_e32 v177, 0xffff0000, v234
	v_lshlrev_b32_e32 v150, 16, v235
	v_and_b32_e32 v151, 0xffff0000, v235
	v_lshlrev_b32_e32 v182, 16, v236
	v_and_b32_e32 v183, 0xffff0000, v236
	v_lshlrev_b32_e32 v152, 16, v237
	v_and_b32_e32 v153, 0xffff0000, v237
	v_pk_fma_f32 v[144:145], v[144:145], v[64:65], v[150:151]
	v_pk_fma_f32 v[142:143], v[142:143], v[62:63], v[176:177]
	v_pk_fma_f32 v[140:141], v[140:141], v[60:61], v[152:153]
	v_pk_fma_f32 v[138:139], v[138:139], v[58:59], v[182:183]
	s_cbranch_vccz .LBB0_1513
	v_cvt_pk_bf16_f32 v150, v142, v143
	v_cvt_pk_bf16_f32 v151, v144, v145
	v_cvt_pk_bf16_f32 v152, v138, v139
	v_cvt_pk_bf16_f32 v153, v140, v141
	s_mov_b64 s[26:27], 0

.LBB0_1517:
	v_lshlrev_b32_e32 v138, 16, v238
	v_and_b32_e32 v139, 0xffff0000, v238
	v_lshlrev_b32_e32 v140, 16, v239
	v_and_b32_e32 v141, 0xffff0000, v239
	v_lshlrev_b32_e32 v142, 16, v240
	v_and_b32_e32 v143, 0xffff0000, v240
	v_lshlrev_b32_e32 v144, 16, v241
	v_and_b32_e32 v145, 0xffff0000, v241
	s_mov_b32 s100, 0x30000
	v_lshl_add_u64 v[216:217], v[180:181], 0, s[100:101]
	global_load_dwordx4 v[234:237], v[216:217], off
	s_nop 0
	global_load_dwordx4 v[238:241], v[216:217], off offset:256
	v_pk_fma_f32 v[136:137], v[136:137], v[56:57], v[140:141]
	v_pk_fma_f32 v[134:135], v[134:135], v[54:55], v[138:139]
	v_pk_fma_f32 v[132:133], v[132:133], v[52:53], v[144:145]
	v_pk_fma_f32 v[130:131], v[130:131], v[50:51], v[142:143]
	s_mov_b64 s[26:27], -1
	s_and_b64 vcc, exec, s[94:95]
	s_cbranch_vccz .LBB0_1519
	v_cvt_pk_bf16_f32 v138, v134, v135
	v_cvt_pk_bf16_f32 v139, v136, v137
	v_cvt_pk_bf16_f32 v140, v130, v131
	v_cvt_pk_bf16_f32 v141, v132, v133
	global_store_dwordx4 v[178:179], v[138:141], off offset:256
	s_mov_b64 s[26:27], 0

.LBB0_1525:
	s_mov_b64 s[26:27], -1
	s_waitcnt lgkmcnt(0)
	s_and_b64 vcc, exec, s[94:95]
	s_waitcnt vmcnt(7)
	v_lshlrev_b32_e32 v140, 16, v242
	v_and_b32_e32 v141, 0xffff0000, v242
	v_lshlrev_b32_e32 v134, 16, v243
	v_and_b32_e32 v135, 0xffff0000, v243
	v_lshlrev_b32_e32 v142, 16, v244
	v_and_b32_e32 v143, 0xffff0000, v244
	v_lshlrev_b32_e32 v136, 16, v245
	v_and_b32_e32 v137, 0xffff0000, v245
	v_pk_fma_f32 v[128:129], v[128:129], v[64:65], v[134:135]
	v_pk_fma_f32 v[126:127], v[126:127], v[62:63], v[140:141]
	v_pk_fma_f32 v[124:125], v[124:125], v[60:61], v[136:137]
	v_pk_fma_f32 v[122:123], v[122:123], v[58:59], v[142:143]
	s_cbranch_vccz .LBB0_1527
	v_add_co_u32_e32 v140, vcc, 0x10000, v178
	v_cvt_pk_bf16_f32 v134, v126, v127
	v_cvt_pk_bf16_f32 v135, v128, v129
	v_cvt_pk_bf16_f32 v136, v122, v123
	v_cvt_pk_bf16_f32 v137, v124, v125
	s_nop 1
	v_addc_co_u32_e32 v141, vcc, 0, v179, vcc
	global_store_dwordx4 v[140:141], v[134:137], off
	s_mov_b64 s[26:27], 0

.LBB0_1531:
	s_waitcnt vmcnt(7)
	v_lshlrev_b32_e32 v122, 16, v246
	v_and_b32_e32 v123, 0xffff0000, v246
	v_lshlrev_b32_e32 v124, 16, v247
	v_and_b32_e32 v125, 0xffff0000, v247
	v_lshlrev_b32_e32 v126, 16, v248
	v_and_b32_e32 v127, 0xffff0000, v248
	v_lshlrev_b32_e32 v128, 16, v249
	v_and_b32_e32 v129, 0xffff0000, v249
	s_mov_b32 s100, 0x80000
	v_lshl_add_u64 v[232:233], v[180:181], 0, s[100:101]
	global_load_dwordx4 v[242:245], v[232:233], off
	s_nop 0
	global_load_dwordx4 v[246:249], v[232:233], off offset:256
	v_pk_fma_f32 v[120:121], v[120:121], v[56:57], v[124:125]
	v_pk_fma_f32 v[118:119], v[118:119], v[54:55], v[122:123]
	v_pk_fma_f32 v[116:117], v[116:117], v[52:53], v[128:129]
	v_pk_fma_f32 v[114:115], v[114:115], v[50:51], v[126:127]
	s_mov_b64 s[26:27], -1
	s_and_b64 vcc, exec, s[94:95]
	s_cbranch_vccz .LBB0_1534
	v_add_co_u32_e32 v126, vcc, 0x10000, v178
	v_cvt_pk_bf16_f32 v122, v118, v119
	v_cvt_pk_bf16_f32 v123, v120, v121
	v_cvt_pk_bf16_f32 v124, v114, v115
	v_cvt_pk_bf16_f32 v125, v116, v117
	s_nop 1
	v_addc_co_u32_e32 v127, vcc, 0, v179, vcc
	global_store_dwordx4 v[126:127], v[122:125], off offset:256
	s_cbranch_execz .LBB0_1535

.LBB0_1539:
	s_mov_b64 s[26:27], -1
	s_waitcnt lgkmcnt(0)
	s_and_b64 vcc, exec, s[94:95]
	s_waitcnt vmcnt(9)
	v_lshlrev_b32_e32 v122, 16, v208
	v_and_b32_e32 v123, 0xffff0000, v208
	v_lshlrev_b32_e32 v118, 16, v209
	v_and_b32_e32 v119, 0xffff0000, v209
	v_lshlrev_b32_e32 v124, 16, v210
	v_and_b32_e32 v125, 0xffff0000, v210
	v_lshlrev_b32_e32 v120, 16, v211
	v_and_b32_e32 v121, 0xffff0000, v211
	v_pk_fma_f32 v[112:113], v[112:113], v[64:65], v[118:119]
	v_pk_fma_f32 v[110:111], v[110:111], v[62:63], v[122:123]
	v_pk_fma_f32 v[108:109], v[108:109], v[60:61], v[120:121]
	v_pk_fma_f32 v[106:107], v[106:107], v[58:59], v[124:125]
	s_cbranch_vccz .LBB0_1541
	v_cvt_pk_bf16_f32 v118, v110, v111
	v_cvt_pk_bf16_f32 v119, v112, v113
	v_cvt_pk_bf16_f32 v120, v106, v107
	v_cvt_pk_bf16_f32 v121, v108, v109
	global_store_dwordx4 v[134:135], v[118:121], off
	s_mov_b64 s[26:27], 0

.LBB0_1545:
	s_waitcnt vmcnt(9)
	v_lshlrev_b32_e32 v106, 16, v212
	v_and_b32_e32 v107, 0xffff0000, v212
	v_lshlrev_b32_e32 v108, 16, v213
	v_and_b32_e32 v109, 0xffff0000, v213
	v_lshlrev_b32_e32 v110, 16, v214
	v_and_b32_e32 v111, 0xffff0000, v214
	v_lshlrev_b32_e32 v112, 16, v215
	v_and_b32_e32 v113, 0xffff0000, v215
	s_mov_b32 s100, 0x90000
	v_lshl_add_u64 v[216:217], v[180:181], 0, s[100:101]
	global_load_dwordx4 v[208:211], v[216:217], off
	s_nop 0
	global_load_dwordx4 v[212:215], v[216:217], off offset:256
	v_pk_fma_f32 v[104:105], v[104:105], v[56:57], v[108:109]
	v_pk_fma_f32 v[102:103], v[102:103], v[54:55], v[106:107]
	v_pk_fma_f32 v[100:101], v[100:101], v[52:53], v[112:113]
	v_pk_fma_f32 v[98:99], v[98:99], v[50:51], v[110:111]
	s_mov_b64 s[26:27], -1
	s_and_b64 vcc, exec, s[94:95]
	s_cbranch_vccz .LBB0_1548
	v_add_co_u32_e32 v110, vcc, 0x20000, v178
	v_cvt_pk_bf16_f32 v106, v102, v103
	v_cvt_pk_bf16_f32 v107, v104, v105
	v_cvt_pk_bf16_f32 v108, v98, v99
	v_cvt_pk_bf16_f32 v109, v100, v101
	s_nop 1
	v_addc_co_u32_e32 v111, vcc, 0, v179, vcc
	global_store_dwordx4 v[110:111], v[106:109], off offset:256
	s_cbranch_execz .LBB0_1549

.LBB0_1553:
	s_mov_b64 s[26:27], -1
	s_waitcnt lgkmcnt(0)
	s_and_b64 vcc, exec, s[94:95]
	s_waitcnt vmcnt(10)
	v_lshlrev_b32_e32 v106, 16, v234
	v_and_b32_e32 v107, 0xffff0000, v234
	v_lshlrev_b32_e32 v102, 16, v235
	v_and_b32_e32 v103, 0xffff0000, v235
	v_lshlrev_b32_e32 v108, 16, v236
	v_and_b32_e32 v109, 0xffff0000, v236
	v_lshlrev_b32_e32 v104, 16, v237
	v_and_b32_e32 v105, 0xffff0000, v237
	v_pk_fma_f32 v[96:97], v[96:97], v[64:65], v[102:103]
	v_pk_fma_f32 v[94:95], v[94:95], v[62:63], v[106:107]
	v_pk_fma_f32 v[92:93], v[92:93], v[60:61], v[104:105]
	v_pk_fma_f32 v[90:91], v[90:91], v[58:59], v[108:109]
	s_cbranch_vccz .LBB0_1555
	v_add_co_u32_e32 v106, vcc, 0x30000, v178
	v_cvt_pk_bf16_f32 v102, v94, v95
	v_cvt_pk_bf16_f32 v103, v96, v97
	v_cvt_pk_bf16_f32 v104, v90, v91
	v_cvt_pk_bf16_f32 v105, v92, v93
	s_nop 1
	v_addc_co_u32_e32 v107, vcc, 0, v179, vcc
	global_store_dwordx4 v[106:107], v[102:105], off
	s_mov_b64 s[26:27], 0

.LBB0_1559:
	s_waitcnt vmcnt(10)
	v_lshlrev_b32_e32 v90, 16, v238
	v_and_b32_e32 v91, 0xffff0000, v238
	v_lshlrev_b32_e32 v92, 16, v239
	v_and_b32_e32 v93, 0xffff0000, v239
	v_lshlrev_b32_e32 v94, 16, v240
	v_and_b32_e32 v95, 0xffff0000, v240
	v_lshlrev_b32_e32 v96, 16, v241
	v_and_b32_e32 v97, 0xffff0000, v241
	s_mov_b32 s100, 0xa0000
	v_lshl_add_u64 v[232:233], v[180:181], 0, s[100:101]
	global_load_dwordx4 v[234:237], v[232:233], off
	s_nop 0
	global_load_dwordx4 v[238:241], v[232:233], off offset:256
	v_pk_fma_f32 v[88:89], v[88:89], v[56:57], v[92:93]
	v_pk_fma_f32 v[86:87], v[86:87], v[54:55], v[90:91]
	v_pk_fma_f32 v[84:85], v[84:85], v[52:53], v[96:97]
	v_pk_fma_f32 v[82:83], v[82:83], v[50:51], v[94:95]
	s_mov_b64 s[26:27], -1
	s_and_b64 vcc, exec, s[94:95]
	s_cbranch_vccz .LBB0_1562
	v_add_co_u32_e32 v94, vcc, 0x30000, v178
	v_cvt_pk_bf16_f32 v90, v86, v87
	v_cvt_pk_bf16_f32 v91, v88, v89
	v_cvt_pk_bf16_f32 v92, v82, v83
	v_cvt_pk_bf16_f32 v93, v84, v85
	s_nop 1
	v_addc_co_u32_e32 v95, vcc, 0, v179, vcc
	global_store_dwordx4 v[94:95], v[90:93], off offset:256
	s_cbranch_execz .LBB0_1563

.LBB0_1567:
	s_mov_b64 s[26:27], -1
	s_waitcnt lgkmcnt(0)
	s_and_b64 vcc, exec, s[94:95]
	s_waitcnt vmcnt(10)
	v_lshlrev_b32_e32 v90, 16, v242
	v_and_b32_e32 v91, 0xffff0000, v242
	v_lshlrev_b32_e32 v86, 16, v243
	v_and_b32_e32 v87, 0xffff0000, v243
	v_lshlrev_b32_e32 v92, 16, v244
	v_and_b32_e32 v93, 0xffff0000, v244
	v_lshlrev_b32_e32 v88, 16, v245
	v_and_b32_e32 v89, 0xffff0000, v245
	v_pk_fma_f32 v[80:81], v[80:81], v[64:65], v[86:87]
	v_pk_fma_f32 v[78:79], v[78:79], v[62:63], v[90:91]
	v_pk_fma_f32 v[76:77], v[76:77], v[60:61], v[88:89]
	v_pk_fma_f32 v[74:75], v[74:75], v[58:59], v[92:93]
	s_cbranch_vccz .LBB0_1569
	v_add_co_u32_e32 v90, vcc, 0x80000, v178
	v_cvt_pk_bf16_f32 v86, v78, v79
	v_cvt_pk_bf16_f32 v87, v80, v81
	v_cvt_pk_bf16_f32 v88, v74, v75
	v_cvt_pk_bf16_f32 v89, v76, v77
	s_nop 1
	v_addc_co_u32_e32 v91, vcc, 0, v179, vcc
	global_store_dwordx4 v[90:91], v[86:89], off
	s_mov_b64 s[26:27], 0

.LBB0_1573:
	s_waitcnt vmcnt(10)
	v_lshlrev_b32_e32 v74, 16, v246
	v_and_b32_e32 v75, 0xffff0000, v246
	v_lshlrev_b32_e32 v76, 16, v247
	v_and_b32_e32 v77, 0xffff0000, v247
	v_lshlrev_b32_e32 v78, 16, v248
	v_and_b32_e32 v79, 0xffff0000, v248
	v_lshlrev_b32_e32 v80, 16, v249
	v_and_b32_e32 v81, 0xffff0000, v249
	s_mov_b32 s100, 0xb0000
	v_lshl_add_u64 v[216:217], v[180:181], 0, s[100:101]
	global_load_dwordx4 v[242:245], v[216:217], off
	s_nop 0
	global_load_dwordx4 v[246:249], v[216:217], off offset:256
	v_pk_fma_f32 v[72:73], v[72:73], v[56:57], v[76:77]
	v_pk_fma_f32 v[70:71], v[70:71], v[54:55], v[74:75]
	v_pk_fma_f32 v[68:69], v[68:69], v[52:53], v[80:81]
	v_pk_fma_f32 v[66:67], v[66:67], v[50:51], v[78:79]
	s_mov_b64 s[26:27], -1
	s_and_b64 vcc, exec, s[94:95]
	s_cbranch_vccz .LBB0_1576
	v_add_co_u32_e32 v78, vcc, 0x80000, v178
	v_cvt_pk_bf16_f32 v74, v70, v71
	v_cvt_pk_bf16_f32 v75, v72, v73
	v_cvt_pk_bf16_f32 v76, v66, v67
	v_cvt_pk_bf16_f32 v77, v68, v69
	s_nop 1
	v_addc_co_u32_e32 v79, vcc, 0, v179, vcc
	global_store_dwordx4 v[78:79], v[74:77], off offset:256
	s_cbranch_execz .LBB0_1577

.LBB0_1581:
	s_mov_b64 s[26:27], -1
	s_waitcnt lgkmcnt(0)
	s_and_b64 vcc, exec, s[94:95]
	s_waitcnt vmcnt(10)
	v_lshlrev_b32_e32 v74, 16, v208
	v_and_b32_e32 v75, 0xffff0000, v208
	v_lshlrev_b32_e32 v70, 16, v209
	v_and_b32_e32 v71, 0xffff0000, v209
	v_lshlrev_b32_e32 v76, 16, v210
	v_and_b32_e32 v77, 0xffff0000, v210
	v_lshlrev_b32_e32 v72, 16, v211
	v_and_b32_e32 v73, 0xffff0000, v211
	v_pk_fma_f32 v[48:49], v[48:49], v[64:65], v[70:71]
	v_pk_fma_f32 v[46:47], v[46:47], v[62:63], v[74:75]
	v_pk_fma_f32 v[44:45], v[44:45], v[60:61], v[72:73]
	v_pk_fma_f32 v[42:43], v[42:43], v[58:59], v[76:77]
	s_cbranch_vccz .LBB0_1583
	v_add_co_u32_e32 v74, vcc, 0x90000, v178
	v_cvt_pk_bf16_f32 v70, v46, v47
	v_cvt_pk_bf16_f32 v71, v48, v49
	v_cvt_pk_bf16_f32 v72, v42, v43
	v_cvt_pk_bf16_f32 v73, v44, v45
	s_nop 1
	v_addc_co_u32_e32 v75, vcc, 0, v179, vcc
	global_store_dwordx4 v[74:75], v[70:73], off
	s_mov_b64 s[26:27], 0

.LBB0_1587:
	s_waitcnt vmcnt(10)
	v_lshlrev_b32_e32 v42, 16, v212
	v_and_b32_e32 v43, 0xffff0000, v212
	v_lshlrev_b32_e32 v44, 16, v213
	v_and_b32_e32 v45, 0xffff0000, v213
	v_lshlrev_b32_e32 v46, 16, v214
	v_and_b32_e32 v47, 0xffff0000, v214
	v_lshlrev_b32_e32 v48, 16, v215
	v_and_b32_e32 v49, 0xffff0000, v215
	v_pk_fma_f32 v[40:41], v[40:41], v[56:57], v[44:45]
	v_pk_fma_f32 v[38:39], v[38:39], v[54:55], v[42:43]
	v_pk_fma_f32 v[36:37], v[36:37], v[52:53], v[48:49]
	v_pk_fma_f32 v[34:35], v[34:35], v[50:51], v[46:47]
	s_mov_b64 s[26:27], -1
	s_and_b64 vcc, exec, s[94:95]
	s_cbranch_vccz .LBB0_1590
	v_add_co_u32_e32 v46, vcc, 0x90000, v178
	v_cvt_pk_bf16_f32 v42, v38, v39
	v_cvt_pk_bf16_f32 v43, v40, v41
	v_cvt_pk_bf16_f32 v44, v34, v35
	v_cvt_pk_bf16_f32 v45, v36, v37
	s_nop 1
	v_addc_co_u32_e32 v47, vcc, 0, v179, vcc
	global_store_dwordx4 v[46:47], v[42:45], off offset:256
	s_cbranch_execz .LBB0_1591

.LBB0_1595:
	s_mov_b64 s[26:27], -1
	s_waitcnt lgkmcnt(0)
	s_and_b64 vcc, exec, s[94:95]
	s_waitcnt vmcnt(8)
	v_lshlrev_b32_e32 v42, 16, v234
	v_and_b32_e32 v43, 0xffff0000, v234
	v_lshlrev_b32_e32 v38, 16, v235
	v_and_b32_e32 v39, 0xffff0000, v235
	v_lshlrev_b32_e32 v44, 16, v236
	v_and_b32_e32 v45, 0xffff0000, v236
	v_lshlrev_b32_e32 v40, 16, v237
	v_and_b32_e32 v41, 0xffff0000, v237
	v_pk_fma_f32 v[32:33], v[32:33], v[64:65], v[38:39]
	v_pk_fma_f32 v[30:31], v[30:31], v[62:63], v[42:43]
	v_pk_fma_f32 v[28:29], v[28:29], v[60:61], v[40:41]
	v_pk_fma_f32 v[26:27], v[26:27], v[58:59], v[44:45]
	s_cbranch_vccz .LBB0_1597
	v_add_co_u32_e32 v42, vcc, 0xa0000, v178
	v_cvt_pk_bf16_f32 v38, v30, v31
	v_cvt_pk_bf16_f32 v39, v32, v33
	v_cvt_pk_bf16_f32 v40, v26, v27
	v_cvt_pk_bf16_f32 v41, v28, v29
	s_nop 1
	v_addc_co_u32_e32 v43, vcc, 0, v179, vcc
	global_store_dwordx4 v[42:43], v[38:41], off
	s_mov_b64 s[26:27], 0

.LBB0_1601:
	s_waitcnt vmcnt(8)
	v_lshlrev_b32_e32 v26, 16, v238
	v_and_b32_e32 v27, 0xffff0000, v238
	v_lshlrev_b32_e32 v28, 16, v239
	v_and_b32_e32 v29, 0xffff0000, v239
	v_lshlrev_b32_e32 v30, 16, v240
	v_and_b32_e32 v31, 0xffff0000, v240
	v_lshlrev_b32_e32 v32, 16, v241
	v_and_b32_e32 v33, 0xffff0000, v241
	v_pk_fma_f32 v[24:25], v[24:25], v[56:57], v[28:29]
	v_pk_fma_f32 v[22:23], v[22:23], v[54:55], v[26:27]
	v_pk_fma_f32 v[20:21], v[20:21], v[52:53], v[32:33]
	v_pk_fma_f32 v[18:19], v[18:19], v[50:51], v[30:31]
	s_mov_b64 s[26:27], -1
	s_and_b64 vcc, exec, s[94:95]
	s_cbranch_vccz .LBB0_1604
	v_add_co_u32_e32 v30, vcc, 0xa0000, v178
	v_cvt_pk_bf16_f32 v26, v22, v23
	v_cvt_pk_bf16_f32 v27, v24, v25
	v_cvt_pk_bf16_f32 v28, v18, v19
	v_cvt_pk_bf16_f32 v29, v20, v21
	s_nop 1
	v_addc_co_u32_e32 v31, vcc, 0, v179, vcc
	global_store_dwordx4 v[30:31], v[26:29], off offset:256
	s_cbranch_execz .LBB0_1605

.LBB0_1609:
	s_mov_b64 s[26:27], -1
	s_waitcnt lgkmcnt(0)
	s_and_b64 vcc, exec, s[94:95]
	s_waitcnt vmcnt(6)
	v_lshlrev_b32_e32 v26, 16, v242
	v_and_b32_e32 v27, 0xffff0000, v242
	v_lshlrev_b32_e32 v22, 16, v243
	v_and_b32_e32 v23, 0xffff0000, v243
	v_lshlrev_b32_e32 v28, 16, v244
	v_and_b32_e32 v29, 0xffff0000, v244
	v_lshlrev_b32_e32 v24, 16, v245
	v_and_b32_e32 v25, 0xffff0000, v245
	v_pk_fma_f32 v[16:17], v[16:17], v[64:65], v[22:23]
	v_pk_fma_f32 v[14:15], v[14:15], v[62:63], v[26:27]
	v_pk_fma_f32 v[12:13], v[12:13], v[60:61], v[24:25]
	v_pk_fma_f32 v[10:11], v[10:11], v[58:59], v[28:29]
	s_cbranch_vccz .LBB0_1611
	v_add_co_u32_e32 v26, vcc, 0xb0000, v178
	v_cvt_pk_bf16_f32 v22, v14, v15
	v_cvt_pk_bf16_f32 v23, v16, v17
	v_cvt_pk_bf16_f32 v24, v10, v11
	v_cvt_pk_bf16_f32 v25, v12, v13
	s_nop 1
	v_addc_co_u32_e32 v27, vcc, 0, v179, vcc
	global_store_dwordx4 v[26:27], v[22:25], off
	s_mov_b64 s[26:27], 0

.LBB0_1615:
	s_waitcnt vmcnt(6)
	v_lshlrev_b32_e32 v10, 16, v246
	v_and_b32_e32 v11, 0xffff0000, v246
	v_lshlrev_b32_e32 v12, 16, v247
	v_and_b32_e32 v13, 0xffff0000, v247
	v_lshlrev_b32_e32 v14, 16, v248
	v_and_b32_e32 v15, 0xffff0000, v248
	v_lshlrev_b32_e32 v16, 16, v249
	v_and_b32_e32 v17, 0xffff0000, v249
	v_pk_fma_f32 v[8:9], v[8:9], v[56:57], v[12:13]
	v_pk_fma_f32 v[6:7], v[6:7], v[54:55], v[10:11]
	v_pk_fma_f32 v[4:5], v[4:5], v[52:53], v[16:17]
	v_pk_fma_f32 v[2:3], v[2:3], v[50:51], v[14:15]
	s_mov_b64 s[26:27], -1
	s_and_b64 vcc, exec, s[94:95]
	s_cbranch_vccz .LBB0_1618
	v_add_co_u32_e32 v14, vcc, 0xb0000, v178
	v_cvt_pk_bf16_f32 v10, v6, v7
	v_cvt_pk_bf16_f32 v11, v8, v9
	v_cvt_pk_bf16_f32 v12, v2, v3
	v_cvt_pk_bf16_f32 v13, v4, v5
	s_nop 1
	v_addc_co_u32_e32 v15, vcc, 0, v179, vcc
	global_store_dwordx4 v[14:15], v[10:13], off offset:256
	s_cbranch_execz .LBB0_1619
